# grid barrier: group-last blocks bump the top counter without waiting for the return and every block polls that counter (one atomic round trip and the 8-flag fan-out removed)
# speedup vs baseline: 1.0077x; 1.0021x over previous
; __global__ void __launch_bounds__(256, 2) mega(Params p, int ph_lo, int ph_hi) {
;     ...
;     if (ph + 1 < ph_hi && s != 5) grid.sync();
.Lgs_fast:
	buffer_wbl2 sc1
	s_sub_u32 s6, s4, 0xc8
	s_subb_u32 s7, s5, 0
	s_load_dwordx2 s[6:7], s[6:7], 0x0
	v_mov_b32_e32 v2, 0
	v_mov_b32_e32 v3, 1
	s_and_b32 s8, s101, 7
	s_mul_i32 s8, s8, 0xd00
	s_addk_i32 s8, 0x280
	s_waitcnt vmcnt(0) lgkmcnt(0)
	s_sub_u32 s10, s6, s8
	s_subb_u32 s11, s7, 0
	global_atomic_add v0, v2, v3, s[10:11] sc0
	s_sub_u32 s10, s6, 0xd280
	s_subb_u32 s11, s7, 0
	s_waitcnt vmcnt(0)
	v_readfirstlane_b32 s8, v0
	s_lshr_b32 s9, s8, 6
	s_and_b32 s8, s8, 63
	s_cmp_lg_u32 s8, 63
	s_cbranch_scc1 .Lgs_poll
	global_atomic_add v2, v3, s[10:11]
.Lgs_poll:
	global_load_dword v0, v2, s[10:11] sc1
	s_waitcnt vmcnt(0)
	v_readfirstlane_b32 s8, v0
	s_lshr_b32 s8, s8, 3
	s_cmp_lg_u32 s8, s9
	s_cbranch_scc1 .Lgs_to_inv
	s_sleep 1
	s_branch .Lgs_poll
